# HL hyena pass A: all 38 tap/weight loads hoisted into 4 groups (was 20 serialized load-wait round trips)
# baseline (speedup 1.0000x reference)
.LBB0_788:
	s_or_b64 exec, exec, s[36:37]
	s_lshr_b32 s21, s19, 6
	v_ashrrev_i32_e32 v23, 31, v22
	s_lshl_b32 s19, s21, 10
	v_lshlrev_b32_e32 v24, 14, v0
	v_add_u32_e32 v30, -1, v0
	s_addk_i32 s19, 0x1000
	v_and_b32_e32 v24, 0x4000, v24
	v_readlane_b32 s22, v251, 39
	v_lshl_add_u64 v[22:23], v[22:23], 2, s[26:27]
	v_med3_i32 v31, v30, 0, v202
	v_lshlrev_b32_e32 v25, 8, v125
	v_or_b32_e32 v130, s22, v24
	global_load_dword v100, v[22:23], off
	v_or_b32_e32 v22, s19, v31
	v_mov_b64_e32 v[106:107], s[6:7]
	v_and_b32_e32 v129, 0x3e00, v25
	v_add_u32_e32 v24, v121, v130
	s_mov_b32 s22, 0x20000
	v_mad_u64_u32 v[94:95], s[36:37], v22, s0, v[106:107]
	s_lshl_b32 s70, s23, 1
	v_add3_u32 v24, v24, v129, s22
	v_lshl_add_u64 v[22:23], v[94:95], 0, s[70:71]
	v_ashrrev_i32_e32 v25, 31, v24
	v_add_co_u32_e32 v26, vcc, s3, v22
	v_lshl_add_u64 v[24:25], v[24:25], 2, s[34:35]
	s_nop 0
	v_addc_co_u32_e32 v27, vcc, 0, v23, vcc
	global_load_dword v122, v[24:25], off
	s_nop 0
	global_load_dwordx4 v[22:25], v[26:27], off offset:1024
	s_nop 0
	global_load_dwordx4 v[26:29], v[26:27], off offset:3072
	v_cmp_eq_u32_e64 s[36:37], v30, v31
	v_med3_i32 v30, v0, 0, v202
	s_lshl_b32 s23, s23, 2
	s_add_u32 s84, s82, s23
	s_addc_u32 s85, s83, 0
	s_add_u32 s44, s84, 0x1000
	s_addc_u32 s45, s85, 0
	v_mov_b32_e32 v42, s23
	s_add_u32 s86, s80, s23
	s_addc_u32 s87, s81, 0
	v_lshlrev_b32_e32 v132, 1, v0
	v_add_u32_e32 v124, 0x100, v0
	v_add_u32_e32 v137, 0x101, v0
	v_med3_i32 v138, v137, 0, v202
	v_cmp_eq_u32_e64 s[60:61], v137, v138
	v_and_b32_e32 v127, 15, v0
	v_lshlrev_b32_e32 v131, 3, v125
	v_lshrrev_b32_e32 v128, 4, v125
	v_lshlrev_b32_e32 v160, 1, v131
	s_mov_b32 s22, 0
	s_mov_b64 s[90:91], -1
	s_mov_b64 s[92:93], 0
	s_waitcnt vmcnt(4)
	v_or_b32_e32 v174, s19, v30
	v_mad_u64_u32 v[96:97], s[38:39], v174, s0, v[106:107]
	v_lshl_add_u64 v[176:177], v[96:97], 0, s[70:71]
	v_add_co_u32_e32 v172, vcc, s3, v176
	s_nop 1
	v_addc_co_u32_e32 v173, vcc, 0, v177, vcc
	global_load_dwordx4 v[178:181], v[172:173], off offset:1024
	global_load_dwordx4 v[182:185], v[172:173], off offset:3072
	v_add_u32_e32 v174, 1, v0
	v_med3_i32 v31, v174, 0, v202
	v_or_b32_e32 v175, s19, v31
	v_mad_u64_u32 v[98:99], s[40:41], v175, s0, v[106:107]
	v_lshl_add_u64 v[176:177], v[98:99], 0, s[70:71]
	v_add_co_u32_e32 v172, vcc, s3, v176
	s_nop 1
	v_addc_co_u32_e32 v173, vcc, 0, v177, vcc
	global_load_dwordx4 v[204:207], v[172:173], off offset:1024
	global_load_dwordx4 v[208:211], v[172:173], off offset:3072
	global_load_dwordx4 v[172:175], v161, s[44:45] offset:16
	global_load_dwordx4 v[212:215], v195, s[84:85]
	global_load_dwordx4 v[216:219], v42, s[82:83] offset:16
	global_load_dwordx4 v[34:37], v42, s[82:83]
	global_load_dwordx4 v[38:41], v42, s[80:81] offset:16
	global_load_dwordx4 v[50:53], v42, s[80:81]
	s_add_u32 s44, s86, 0x1000
	s_addc_u32 s45, s87, 0
	global_load_dwordx4 v[220:223], v161, s[44:45] offset:16
	global_load_dwordx4 v[54:57], v195, s[86:87]
	s_add_u32 s44, s86, 0x1800
	s_addc_u32 s45, s87, 0
	global_load_dwordx4 v[224:227], v161, s[44:45] offset:16
	global_load_dwordx4 v[228:231], v195, s[86:87] offset:2048
	s_add_u32 s44, s86, 0x2800
	s_addc_u32 s45, s87, 0
	global_load_dwordx4 v[232:235], v161, s[44:45] offset:16
	global_load_dwordx4 v[70:73], v196, s[86:87] offset:2048
	s_add_u32 s44, s86, 0x3000
	s_addc_u32 s45, s87, 0
	global_load_dwordx4 v[236:239], v161, s[44:45] offset:16
	global_load_dwordx4 v[240:243], v197, s[86:87]
	s_add_u32 s44, s86, 0x4000
	s_addc_u32 s45, s87, 0
	global_load_dwordx4 v[244:247], v161, s[44:45] offset:16
	global_load_dwordx4 v[82:85], v198, s[86:87]
	s_waitcnt vmcnt(21)
	v_cndmask_b32_e64 v49, 0, v22, s[36:37]
	v_or_b32_e32 v22, s19, v30
	v_mad_u64_u32 v[96:97], s[38:39], v22, s0, v[106:107]
	v_cndmask_b32_e64 v48, 0, v23, s[36:37]
	s_nop 0
	s_waitcnt vmcnt(20)
	v_cndmask_b32_e64 v61, 0, v26, s[36:37]
	s_nop 0
	v_cndmask_b32_e64 v60, 0, v27, s[36:37]
	s_nop 0
	s_nop 0
	v_cndmask_b32_e64 v46, 0, v25, s[36:37]
	v_cndmask_b32_e64 v47, 0, v24, s[36:37]
	v_cndmask_b32_e64 v58, 0, v29, s[36:37]
	v_cndmask_b32_e64 v59, 0, v28, s[36:37]
	s_nop 0
	s_nop 0
	s_nop 0
	v_cmp_eq_u32_e64 s[38:39], v0, v30
	v_add_u32_e32 v30, 1, v0
	v_med3_i32 v31, v30, 0, v202
	v_lshlrev_b32_e32 v43, 16, v49
	v_and_b32_e32 v49, 0xffff0000, v49
	v_lshlrev_b32_e32 v66, 16, v61
	s_waitcnt vmcnt(19)
	v_cndmask_b32_e64 v65, 0, v178, s[38:39]
	v_or_b32_e32 v22, s19, v31
	v_mad_u64_u32 v[98:99], s[40:41], v22, s0, v[106:107]
	v_cndmask_b32_e64 v64, 0, v179, s[38:39]
	s_nop 0
	s_waitcnt vmcnt(18)
	v_cndmask_b32_e64 v77, 0, v182, s[38:39]
	s_nop 0
	v_cndmask_b32_e64 v76, 0, v183, s[38:39]
	s_nop 0
	s_nop 0
	v_cndmask_b32_e64 v62, 0, v181, s[38:39]
	v_cndmask_b32_e64 v63, 0, v180, s[38:39]
	v_cndmask_b32_e64 v74, 0, v185, s[38:39]
	v_cndmask_b32_e64 v75, 0, v184, s[38:39]
	s_nop 0
	s_nop 0
	s_nop 0
	v_cmp_eq_u32_e64 s[40:41], v30, v31
	v_lshlrev_b32_e32 v78, 16, v77
	s_waitcnt vmcnt(17)
	v_cndmask_b32_e64 v86, 0, v207, s[40:41]
	v_cndmask_b32_e64 v88, 0, v206, s[40:41]
	v_cndmask_b32_e64 v90, 0, v205, s[40:41]
	v_cndmask_b32_e64 v93, 0, v204, s[40:41]
	s_waitcnt vmcnt(16)
	v_cndmask_b32_e64 v87, 0, v211, s[40:41]
	v_cndmask_b32_e64 v89, 0, v210, s[40:41]
	v_cndmask_b32_e64 v91, 0, v209, s[40:41]
	v_cndmask_b32_e64 v101, 0, v208, s[40:41]
	s_nop 0
	s_nop 0
	s_nop 0
	s_nop 0
	s_nop 0
	s_nop 0
	s_nop 0
	s_nop 0
	v_lshlrev_b32_e32 v119, 16, v101
	s_waitcnt vmcnt(10)
	v_fma_f32 v92, v50, v43, v34
	s_nop 0
	s_nop 0
	v_fma_f32 v114, v51, v49, v35
	v_and_b32_e32 v49, 0xffff0000, v61
	s_nop 0
	s_nop 0
	s_waitcnt vmcnt(8)
	v_fma_f32 v117, v55, v49, v213
	v_lshlrev_b32_e32 v49, 16, v48
	v_and_b32_e32 v48, 0xffff0000, v48
	v_fma_f32 v110, v53, v48, v37
	v_and_b32_e32 v48, 0xffff0000, v60
	v_fma_f32 v115, v57, v48, v215
	v_lshlrev_b32_e32 v48, 16, v47
	v_and_b32_e32 v47, 0xffff0000, v47
	v_fma_f32 v104, v39, v47, v217
	v_and_b32_e32 v47, 0xffff0000, v59
	v_fma_f32 v111, v221, v47, v173
	v_lshlrev_b32_e32 v47, 16, v46
	v_and_b32_e32 v46, 0xffff0000, v46
	v_fma_f32 v112, v52, v49, v36
	v_lshlrev_b32_e32 v49, 16, v60
	v_fma_f32 v108, v38, v48, v216
	v_lshlrev_b32_e32 v48, 16, v59
	v_fma_f32 v103, v40, v47, v218
	v_lshlrev_b32_e32 v47, 16, v58
	v_fma_f32 v102, v41, v46, v219
	v_and_b32_e32 v46, 0xffff0000, v58
	v_fma_f32 v118, v54, v66, v212
	v_fma_f32 v116, v56, v49, v214
	v_fma_f32 v113, v220, v48, v172
	v_fma_f32 v109, v222, v47, v174
	v_fma_f32 v105, v223, v46, v175
	s_nop 0
	s_nop 0
	s_nop 0
	v_lshlrev_b32_e32 v58, 16, v65
	s_nop 0
	v_and_b32_e32 v65, 0xffff0000, v65
	s_waitcnt vmcnt(6)
	v_fmac_f32_e32 v92, v228, v58
	s_nop 0
	s_nop 0
	v_fmac_f32_e32 v114, v229, v65
	v_and_b32_e32 v65, 0xffff0000, v77
	s_nop 0
	s_nop 0
	s_waitcnt vmcnt(4)
	v_fmac_f32_e32 v117, v71, v65
	v_lshlrev_b32_e32 v65, 16, v64
	v_and_b32_e32 v64, 0xffff0000, v64
	v_fmac_f32_e32 v110, v231, v64
	v_and_b32_e32 v64, 0xffff0000, v76
	v_fmac_f32_e32 v115, v73, v64
	v_lshlrev_b32_e32 v64, 16, v63
	v_and_b32_e32 v63, 0xffff0000, v63
	v_fmac_f32_e32 v104, v225, v63
	v_and_b32_e32 v63, 0xffff0000, v75
	v_fmac_f32_e32 v111, v233, v63
	v_lshlrev_b32_e32 v63, 16, v62
	v_and_b32_e32 v62, 0xffff0000, v62
	v_fmac_f32_e32 v112, v230, v65
	v_lshlrev_b32_e32 v65, 16, v76
	v_fmac_f32_e32 v108, v224, v64
	v_lshlrev_b32_e32 v64, 16, v75
	v_fmac_f32_e32 v103, v226, v63
	v_lshlrev_b32_e32 v63, 16, v74
	v_fmac_f32_e32 v102, v227, v62
	v_and_b32_e32 v62, 0xffff0000, v74
	v_fmac_f32_e32 v118, v70, v78
	v_fmac_f32_e32 v116, v72, v65
	v_fmac_f32_e32 v113, v232, v64
	v_fmac_f32_e32 v109, v234, v63
	v_fmac_f32_e32 v105, v235, v62
	s_nop 0
	s_nop 0
	s_nop 0
	v_lshlrev_b32_e32 v74, 16, v93
	s_nop 0
	v_and_b32_e32 v93, 0xffff0000, v93
	s_waitcnt vmcnt(2)
	v_fmac_f32_e32 v92, v240, v74
	s_nop 0
	s_nop 0
	v_fmac_f32_e32 v114, v241, v93
	v_and_b32_e32 v93, 0xffff0000, v101
	v_add_u32_e32 v101, s17, v132
	s_waitcnt vmcnt(0)
	v_fmac_f32_e32 v117, v83, v93
	s_waitcnt vmcnt(0)
	v_add_u32_e32 v248, 0xff, v0
	v_med3_i32 v249, v248, 0, v202
	v_or_b32_e32 v254, s19, v249
	v_mad_u64_u32 v[42:43], s[44:45], v254, s0, v[106:107]
	v_lshl_add_u64 v[44:45], v[42:43], 0, s[70:71]
	v_add_co_u32_e32 v158, vcc, s3, v44
	s_nop 1
	v_addc_co_u32_e32 v159, vcc, 0, v45, vcc
	global_load_dwordx4 v[46:49], v[158:159], off offset:1024
	global_load_dwordx4 v[58:61], v[158:159], off offset:3072
	v_med3_i32 v248, v124, 0, v202
	v_or_b32_e32 v249, s19, v248
	v_mad_u64_u32 v[254:255], s[44:45], v249, s0, v[106:107]
	v_lshl_add_u64 v[42:43], v[254:255], 0, s[70:71]
	v_add_co_u32_e32 v158, vcc, s3, v42
	s_nop 1
	v_addc_co_u32_e32 v159, vcc, 0, v43, vcc
	global_load_dwordx4 v[62:65], v[158:159], off offset:1024
	global_load_dwordx4 v[66:69], v[158:159], off offset:3072
	v_or_b32_e32 v248, s19, v138
	v_mad_u64_u32 v[254:255], s[44:45], v248, s0, v[106:107]
	v_lshl_add_u64 v[42:43], v[254:255], 0, s[70:71]
	v_add_co_u32_e32 v158, vcc, s3, v42
	s_nop 1
	v_addc_co_u32_e32 v159, vcc, 0, v43, vcc
	global_load_dwordx4 v[74:77], v[158:159], off offset:1024
	global_load_dwordx4 v[78:81], v[158:159], off offset:3072
	v_add_u32_e32 v248, 0x1ff, v0
	v_med3_i32 v249, v248, 0, v202
	v_or_b32_e32 v254, s19, v249
	v_mad_u64_u32 v[42:43], s[44:45], v254, s0, v[106:107]
	v_lshl_add_u64 v[44:45], v[42:43], 0, s[70:71]
	v_add_co_u32_e32 v158, vcc, s3, v44
	s_nop 1
	v_addc_co_u32_e32 v159, vcc, 0, v45, vcc
	global_load_dwordx4 v[154:157], v[158:159], off offset:1024
	global_load_dwordx4 v[176:179], v[158:159], off offset:3072
	v_add_u32_e32 v248, 0x200, v0
	v_med3_i32 v249, v248, 0, v202
	v_or_b32_e32 v254, s19, v249
	v_mad_u64_u32 v[42:43], s[44:45], v254, s0, v[106:107]
	v_lshl_add_u64 v[44:45], v[42:43], 0, s[70:71]
	v_add_co_u32_e32 v158, vcc, s3, v44
	s_nop 1
	v_addc_co_u32_e32 v159, vcc, 0, v45, vcc
	global_load_dwordx4 v[180:183], v[158:159], off offset:1024
	global_load_dwordx4 v[184:187], v[158:159], off offset:3072
	v_add_u32_e32 v248, 0x201, v0
	v_med3_i32 v249, v248, 0, v202
	v_or_b32_e32 v254, s19, v249
	v_mad_u64_u32 v[42:43], s[44:45], v254, s0, v[106:107]
	v_lshl_add_u64 v[44:45], v[42:43], 0, s[70:71]
	v_add_co_u32_e32 v158, vcc, s3, v44
	s_nop 1
	v_addc_co_u32_e32 v159, vcc, 0, v45, vcc
	global_load_dwordx4 v[204:207], v[158:159], off offset:1024
	global_load_dwordx4 v[208:211], v[158:159], off offset:3072
	v_lshlrev_b32_e32 v93, 16, v90
	v_and_b32_e32 v90, 0xffff0000, v90
	v_fmac_f32_e32 v110, v243, v90
	v_and_b32_e32 v90, 0xffff0000, v91
	v_fmac_f32_e32 v115, v85, v90
	v_lshlrev_b32_e32 v90, 16, v88
	v_and_b32_e32 v88, 0xffff0000, v88
	v_fmac_f32_e32 v104, v237, v88
	v_and_b32_e32 v88, 0xffff0000, v89
	v_fmac_f32_e32 v111, v245, v88
	v_lshlrev_b32_e32 v88, 16, v86
	v_and_b32_e32 v86, 0xffff0000, v86
	v_fmac_f32_e32 v118, v82, v119
	v_fmac_f32_e32 v102, v239, v86
	v_and_b32_e32 v86, 0xffff0000, v87
	v_fmac_f32_e32 v105, v247, v86
	v_bfe_u32 v86, v118, 16, 1
	v_add3_u32 v86, v118, v86, s94
	ds_write_b16_d16_hi v101, v86 offset:512
	v_bfe_u32 v86, v92, 16, 1
	v_add3_u32 v86, v92, v86, s94
	ds_write_b16_d16_hi v101, v86 offset:24576
	v_bfe_u32 v86, v117, 16, 1
	v_add3_u32 v86, v117, v86, s94
	v_fmac_f32_e32 v112, v242, v93
	v_lshlrev_b32_e32 v93, 16, v91
	ds_write_b16_d16_hi v101, v86 offset:3584
	v_bfe_u32 v86, v114, 16, 1
	v_fmac_f32_e32 v116, v84, v93
	v_add3_u32 v86, v114, v86, s94
	ds_write_b16_d16_hi v101, v86 offset:26624
	v_bfe_u32 v86, v116, 16, 1
	v_add3_u32 v86, v116, v86, s94
	ds_write_b16_d16_hi v101, v86 offset:6656
	v_bfe_u32 v86, v112, 16, 1
	v_add3_u32 v86, v112, v86, s94
	ds_write_b16_d16_hi v101, v86 offset:28672
	v_bfe_u32 v86, v115, 16, 1
	v_add3_u32 v86, v115, v86, s94
	v_fmac_f32_e32 v108, v236, v90
	v_lshlrev_b32_e32 v90, 16, v89
	ds_write_b16_d16_hi v101, v86 offset:9728
	v_bfe_u32 v86, v110, 16, 1
	v_fmac_f32_e32 v113, v244, v90
	v_add3_u32 v86, v110, v86, s94
	ds_write_b16_d16_hi v101, v86 offset:30720
	v_bfe_u32 v86, v113, 16, 1
	v_add3_u32 v86, v113, v86, s94
	ds_write_b16_d16_hi v101, v86 offset:12800
	v_bfe_u32 v86, v108, 16, 1
	v_add3_u32 v86, v108, v86, s94
	ds_write_b16_d16_hi v101, v86 offset:32768
	v_bfe_u32 v86, v111, 16, 1
	v_add3_u32 v86, v111, v86, s94
	v_fmac_f32_e32 v103, v238, v88
	v_lshlrev_b32_e32 v88, 16, v87
	ds_write_b16_d16_hi v101, v86 offset:15872
	v_bfe_u32 v86, v104, 16, 1
	v_fmac_f32_e32 v109, v246, v88
	v_add3_u32 v86, v104, v86, s94
	ds_write_b16_d16_hi v101, v86 offset:34816
	v_bfe_u32 v86, v109, 16, 1
	v_add3_u32 v86, v109, v86, s94
	ds_write_b16_d16_hi v101, v86 offset:18944
	v_bfe_u32 v86, v103, 16, 1
	v_add3_u32 v86, v103, v86, s94
	ds_write_b16_d16_hi v101, v86 offset:36864
	v_bfe_u32 v86, v105, 16, 1
	v_add3_u32 v86, v105, v86, s94
	ds_write_b16_d16_hi v101, v86 offset:22016
	v_bfe_u32 v86, v102, 16, 1
	v_add3_u32 v86, v102, v86, s94
	v_add_u32_e32 v102, 0xff, v0
	v_med3_i32 v103, v102, 0, v202
	ds_write_b16_d16_hi v101, v86 offset:38912
	v_or_b32_e32 v86, s19, v103
	v_mad_u64_u32 v[110:111], s[44:45], v86, s0, v[106:107]
	s_nop 0
	s_nop 0
	v_cmp_eq_u32_e64 s[50:51], v102, v103
	s_nop 0
	s_nop 0
	s_nop 0
	s_nop 0
	s_nop 0
	v_med3_i32 v116, v124, 0, v202
	v_cmp_eq_u32_e64 s[56:57], v124, v116
	s_waitcnt vmcnt(11)
	v_cndmask_b32_e64 v105, 0, v46, s[50:51]
	v_or_b32_e32 v86, s19, v116
	v_mad_u64_u32 v[114:115], s[44:45], v86, s0, v[106:107]
	v_cndmask_b32_e64 v104, 0, v47, s[50:51]
	s_nop 0
	s_waitcnt vmcnt(10)
	v_cndmask_b32_e64 v113, 0, v58, s[50:51]
	s_nop 0
	v_cndmask_b32_e64 v112, 0, v59, s[50:51]
	s_nop 0
	s_nop 0
	v_cndmask_b32_e64 v102, 0, v49, s[50:51]
	v_cndmask_b32_e64 v103, 0, v48, s[50:51]
	v_cndmask_b32_e64 v108, 0, v61, s[50:51]
	v_cndmask_b32_e64 v109, 0, v60, s[50:51]
	s_nop 0
	s_nop 0
	s_nop 0
	v_lshlrev_b32_e32 v137, 16, v105
	v_and_b32_e32 v105, 0xffff0000, v105
	v_fma_f32 v105, v51, v105, v35
	v_lshlrev_b32_e32 v139, 16, v104
	v_and_b32_e32 v104, 0xffff0000, v104
	v_lshlrev_b32_e32 v140, 16, v112
	v_fma_f32 v104, v53, v104, v37
	v_and_b32_e32 v112, 0xffff0000, v112
	v_fma_f32 v112, v57, v112, v215
	v_lshlrev_b32_e32 v141, 16, v103
	v_and_b32_e32 v103, 0xffff0000, v103
	v_lshlrev_b32_e32 v142, 16, v109
	v_fma_f32 v103, v39, v103, v217
	v_and_b32_e32 v109, 0xffff0000, v109
	v_fma_f32 v109, v221, v109, v173
	v_lshlrev_b32_e32 v143, 16, v102
	v_and_b32_e32 v102, 0xffff0000, v102
	v_lshlrev_b32_e32 v144, 16, v108
	v_fma_f32 v102, v41, v102, v219
	v_and_b32_e32 v108, 0xffff0000, v108
	v_fma_f32 v108, v223, v108, v175
	v_fma_f32 v139, v52, v139, v36
	v_fma_f32 v140, v56, v140, v214
	v_fma_f32 v141, v38, v141, v216
	v_fma_f32 v142, v220, v142, v172
	v_fma_f32 v143, v40, v143, v218
	v_fma_f32 v137, v50, v137, v34
	v_fma_f32 v144, v222, v144, v174
	s_waitcnt vmcnt(9)
	v_cndmask_b32_e64 v123, 0, v62, s[56:57]
	v_or_b32_e32 v86, s19, v138
	v_mad_u64_u32 v[118:119], s[44:45], v86, s0, v[106:107]
	v_cndmask_b32_e64 v120, 0, v63, s[56:57]
	s_nop 0
	s_waitcnt vmcnt(8)
	v_cndmask_b32_e64 v136, 0, v66, s[56:57]
	s_nop 0
	v_cndmask_b32_e64 v135, 0, v67, s[56:57]
	s_nop 0
	s_nop 0
	v_cndmask_b32_e64 v116, 0, v65, s[56:57]
	v_cndmask_b32_e64 v117, 0, v64, s[56:57]
	v_cndmask_b32_e64 v133, 0, v69, s[56:57]
	v_cndmask_b32_e64 v134, 0, v68, s[56:57]
	s_nop 0
	s_nop 0
	s_nop 0
	v_lshlrev_b32_e32 v138, 16, v113
	v_and_b32_e32 v113, 0xffff0000, v113
	v_lshlrev_b32_e32 v145, 16, v123
	v_and_b32_e32 v123, 0xffff0000, v123
	v_fma_f32 v113, v55, v113, v213
	v_fmac_f32_e32 v105, v229, v123
	v_and_b32_e32 v123, 0xffff0000, v136
	v_fmac_f32_e32 v113, v71, v123
	v_lshlrev_b32_e32 v123, 16, v120
	v_and_b32_e32 v120, 0xffff0000, v120
	v_fmac_f32_e32 v104, v231, v120
	v_and_b32_e32 v120, 0xffff0000, v135
	v_fmac_f32_e32 v112, v73, v120
	v_lshlrev_b32_e32 v120, 16, v117
	v_and_b32_e32 v117, 0xffff0000, v117
	v_fmac_f32_e32 v103, v225, v117
	v_and_b32_e32 v117, 0xffff0000, v134
	v_fmac_f32_e32 v109, v233, v117
	v_lshlrev_b32_e32 v117, 16, v116
	v_and_b32_e32 v116, 0xffff0000, v116
	s_waitcnt vmcnt(8)
	v_add_u32_e32 v248, 0x2ff, v0
	v_med3_i32 v249, v248, 0, v202
	v_or_b32_e32 v254, s19, v249
	v_mad_u64_u32 v[42:43], s[100:101], v254, s0, v[106:107]
	v_lshl_add_u64 v[44:45], v[42:43], 0, s[70:71]
	v_add_co_u32_e32 v158, vcc, s3, v44
	s_nop 1
	v_addc_co_u32_e32 v159, vcc, 0, v45, vcc
	global_load_dwordx4 v[46:49], v[158:159], off offset:1024
	global_load_dwordx4 v[58:61], v[158:159], off offset:3072
	v_add_u32_e32 v248, 0x300, v0
	v_med3_i32 v249, v248, 0, v202
	v_or_b32_e32 v254, s19, v249
	v_mad_u64_u32 v[42:43], s[46:47], v254, s0, v[106:107]
	v_lshl_add_u64 v[44:45], v[42:43], 0, s[70:71]
	v_add_co_u32_e32 v158, vcc, s3, v44
	s_nop 1
	v_addc_co_u32_e32 v159, vcc, 0, v45, vcc
	global_load_dwordx4 v[62:65], v[158:159], off offset:1024
	global_load_dwordx4 v[66:69], v[158:159], off offset:3072
	v_fmac_f32_e32 v102, v227, v116
	v_and_b32_e32 v116, 0xffff0000, v133
	v_fmac_f32_e32 v108, v235, v116
	v_fmac_f32_e32 v139, v230, v123
	v_lshlrev_b32_e32 v123, 16, v135
	v_fmac_f32_e32 v140, v72, v123
	v_fmac_f32_e32 v141, v224, v120
	v_lshlrev_b32_e32 v120, 16, v134
	v_fmac_f32_e32 v142, v232, v120
	v_fmac_f32_e32 v143, v226, v117
	v_lshlrev_b32_e32 v117, 16, v133
	v_fma_f32 v138, v54, v138, v212
	v_fmac_f32_e32 v137, v228, v145
	v_lshlrev_b32_e32 v145, 16, v136
	v_fmac_f32_e32 v144, v234, v117
	v_fmac_f32_e32 v138, v70, v145
	v_add_u32_e32 v123, 0x200, v0
	s_waitcnt vmcnt(11)
	v_cndmask_b32_e64 v86, 0, v74, s[60:61]
	s_waitcnt vmcnt(10)
	v_cndmask_b32_e64 v90, 0, v78, s[60:61]
	v_lshlrev_b32_e32 v116, 16, v86
	v_and_b32_e32 v86, 0xffff0000, v86
	v_cndmask_b32_e64 v87, 0, v75, s[60:61]
	v_fmac_f32_e32 v105, v241, v86
	v_and_b32_e32 v86, 0xffff0000, v90
	v_cndmask_b32_e64 v91, 0, v79, s[60:61]
	v_fmac_f32_e32 v113, v83, v86
	v_lshlrev_b32_e32 v86, 16, v87
	v_fmac_f32_e32 v139, v242, v86
	v_lshlrev_b32_e32 v86, 16, v91
	v_fmac_f32_e32 v140, v84, v86
	v_and_b32_e32 v86, 0xffff0000, v87
	v_cndmask_b32_e64 v88, 0, v76, s[60:61]
	v_fmac_f32_e32 v104, v243, v86
	v_and_b32_e32 v86, 0xffff0000, v91
	v_cndmask_b32_e64 v92, 0, v80, s[60:61]
	v_fmac_f32_e32 v112, v85, v86
	v_lshlrev_b32_e32 v86, 16, v88
	v_fmac_f32_e32 v141, v236, v86
	v_lshlrev_b32_e32 v86, 16, v92
	v_fmac_f32_e32 v142, v244, v86
	v_and_b32_e32 v86, 0xffff0000, v88
	v_cndmask_b32_e64 v89, 0, v77, s[60:61]
	v_fmac_f32_e32 v103, v237, v86
	v_and_b32_e32 v86, 0xffff0000, v92
	v_cndmask_b32_e64 v93, 0, v81, s[60:61]
	v_fmac_f32_e32 v109, v245, v86
	v_lshlrev_b32_e32 v86, 16, v89
	v_fmac_f32_e32 v143, v238, v86
	v_lshlrev_b32_e32 v86, 16, v93
	v_fmac_f32_e32 v137, v240, v116
	v_lshlrev_b32_e32 v116, 16, v90
	v_fmac_f32_e32 v144, v246, v86
	v_and_b32_e32 v86, 0xffff0000, v89
	v_fmac_f32_e32 v138, v82, v116
	v_fmac_f32_e32 v102, v239, v86
	v_and_b32_e32 v86, 0xffff0000, v93
	v_fmac_f32_e32 v108, v247, v86
	v_bfe_u32 v86, v138, 16, 1
	v_add3_u32 v86, v138, v86, s94
	s_waitcnt vmcnt(10)
	v_add_u32_e32 v248, 0x301, v0
	v_med3_i32 v249, v248, 0, v202
	v_or_b32_e32 v254, s19, v249
	v_mad_u64_u32 v[42:43], s[52:53], v254, s0, v[106:107]
	v_lshl_add_u64 v[44:45], v[42:43], 0, s[70:71]
	v_add_co_u32_e32 v158, vcc, s3, v44
	s_nop 1
	v_addc_co_u32_e32 v159, vcc, 0, v45, vcc
	global_load_dwordx4 v[74:77], v[158:159], off offset:1024
	global_load_dwordx4 v[78:81], v[158:159], off offset:3072
	ds_write_b16_d16_hi v101, v86 offset:1024
	v_bfe_u32 v86, v137, 16, 1
	v_add3_u32 v86, v137, v86, s94
	ds_write_b16_d16_hi v101, v86 offset:25088
	v_bfe_u32 v86, v113, 16, 1
	v_add3_u32 v86, v113, v86, s94
	ds_write_b16_d16_hi v101, v86 offset:4096
	v_bfe_u32 v86, v105, 16, 1
	v_add3_u32 v86, v105, v86, s94
	ds_write_b16_d16_hi v101, v86 offset:27136
	v_bfe_u32 v86, v140, 16, 1
	v_add3_u32 v86, v140, v86, s94
	ds_write_b16_d16_hi v101, v86 offset:7168
	v_bfe_u32 v86, v139, 16, 1
	v_add3_u32 v86, v139, v86, s94
	ds_write_b16_d16_hi v101, v86 offset:29184
	v_bfe_u32 v86, v112, 16, 1
	v_add3_u32 v86, v112, v86, s94
	ds_write_b16_d16_hi v101, v86 offset:10240
	v_bfe_u32 v86, v104, 16, 1
	v_add3_u32 v86, v104, v86, s94
	ds_write_b16_d16_hi v101, v86 offset:31232
	v_bfe_u32 v86, v142, 16, 1
	v_add3_u32 v86, v142, v86, s94
	ds_write_b16_d16_hi v101, v86 offset:13312
	v_bfe_u32 v86, v141, 16, 1
	v_add3_u32 v86, v141, v86, s94
	ds_write_b16_d16_hi v101, v86 offset:33280
	v_bfe_u32 v86, v109, 16, 1
	v_add3_u32 v86, v109, v86, s94
	ds_write_b16_d16_hi v101, v86 offset:16384
	v_bfe_u32 v86, v103, 16, 1
	v_add3_u32 v86, v103, v86, s94
	ds_write_b16_d16_hi v101, v86 offset:35328
	v_bfe_u32 v86, v144, 16, 1
	v_add3_u32 v86, v144, v86, s94
	ds_write_b16_d16_hi v101, v86 offset:19456
	v_bfe_u32 v86, v143, 16, 1
	v_add3_u32 v86, v143, v86, s94
	ds_write_b16_d16_hi v101, v86 offset:37376
	v_bfe_u32 v86, v108, 16, 1
	v_add3_u32 v86, v108, v86, s94
	ds_write_b16_d16_hi v101, v86 offset:22528
	v_bfe_u32 v86, v102, 16, 1
	v_add3_u32 v86, v102, v86, s94
	v_add_u32_e32 v102, 0x1ff, v0
	v_med3_i32 v103, v102, 0, v202
	ds_write_b16_d16_hi v101, v86 offset:39424
	v_or_b32_e32 v86, s19, v103
	v_mad_u64_u32 v[108:109], s[44:45], v86, s0, v[106:107]
	s_nop 0
	s_nop 0
	v_cmp_eq_u32_e64 s[48:49], v102, v103
	s_nop 0
	s_nop 0
	s_nop 0
	s_nop 0
	s_nop 0
	v_med3_i32 v116, v123, 0, v202
	v_add_u32_e32 v144, 0x201, v0
	v_cmp_eq_u32_e64 s[54:55], v123, v116
	v_med3_i32 v145, v144, 0, v202
	v_cmp_eq_u32_e64 s[58:59], v144, v145
	s_waitcnt vmcnt(11)
	v_cndmask_b32_e64 v105, 0, v154, s[48:49]
	v_or_b32_e32 v86, s19, v116
	v_mad_u64_u32 v[112:113], s[44:45], v86, s0, v[106:107]
	v_cndmask_b32_e64 v104, 0, v155, s[48:49]
	s_nop 0
	s_waitcnt vmcnt(10)
	v_cndmask_b32_e64 v135, 0, v176, s[48:49]
	s_nop 0
	v_cndmask_b32_e64 v134, 0, v177, s[48:49]
	s_nop 0
	s_nop 0
	v_cndmask_b32_e64 v102, 0, v157, s[48:49]
	v_cndmask_b32_e64 v103, 0, v156, s[48:49]
	v_cndmask_b32_e64 v120, 0, v179, s[48:49]
	v_cndmask_b32_e64 v133, 0, v178, s[48:49]
	s_nop 0
	s_nop 0
	s_nop 0
	v_lshlrev_b32_e32 v144, 16, v105
	v_lshlrev_b32_e32 v152, 16, v120
	v_and_b32_e32 v120, 0xffff0000, v120
	v_fma_f32 v144, v50, v144, v34
	v_fma_f32 v153, v223, v120, v175
	v_and_b32_e32 v105, 0xffff0000, v105
	v_fma_f32 v105, v51, v105, v35
	v_lshlrev_b32_e32 v146, 16, v104
	v_fma_f32 v146, v52, v146, v36
	v_lshlrev_b32_e32 v147, 16, v134
	v_fma_f32 v147, v56, v147, v214
	v_and_b32_e32 v104, 0xffff0000, v104
	v_fma_f32 v104, v53, v104, v37
	v_and_b32_e32 v134, 0xffff0000, v134
	v_fma_f32 v134, v57, v134, v215
	v_lshlrev_b32_e32 v148, 16, v103
	v_fma_f32 v148, v38, v148, v216
	v_lshlrev_b32_e32 v149, 16, v133
	v_fma_f32 v149, v220, v149, v172
	v_and_b32_e32 v103, 0xffff0000, v103
	v_fma_f32 v103, v39, v103, v217
	v_and_b32_e32 v133, 0xffff0000, v133
	v_fma_f32 v133, v221, v133, v173
	v_lshlrev_b32_e32 v151, 16, v102
	v_fma_f32 v151, v40, v151, v218
	v_fma_f32 v152, v222, v152, v174
	v_and_b32_e32 v102, 0xffff0000, v102
	v_fma_f32 v102, v41, v102, v219
	s_waitcnt vmcnt(9)
	v_cndmask_b32_e64 v139, 0, v180, s[54:55]
	v_or_b32_e32 v86, s19, v145
	v_mad_u64_u32 v[116:117], s[44:45], v86, s0, v[106:107]
	v_cndmask_b32_e64 v138, 0, v181, s[54:55]
	s_nop 0
	s_waitcnt vmcnt(8)
	v_cndmask_b32_e64 v143, 0, v184, s[54:55]
	s_nop 0
	v_cndmask_b32_e64 v142, 0, v185, s[54:55]
	s_nop 0
	s_nop 0
	v_cndmask_b32_e64 v136, 0, v183, s[54:55]
	v_cndmask_b32_e64 v137, 0, v182, s[54:55]
	v_cndmask_b32_e64 v140, 0, v187, s[54:55]
	v_cndmask_b32_e64 v141, 0, v186, s[54:55]
	s_nop 0
	s_nop 0
	s_nop 0
	v_lshlrev_b32_e32 v145, 16, v135
	v_lshlrev_b32_e32 v120, 16, v139
	v_fma_f32 v145, v54, v145, v212
	v_fmac_f32_e32 v144, v228, v120
	v_lshlrev_b32_e32 v120, 16, v143
	v_and_b32_e32 v135, 0xffff0000, v135
	v_fmac_f32_e32 v145, v70, v120
	v_and_b32_e32 v120, 0xffff0000, v139
	v_fma_f32 v135, v55, v135, v213
	v_fmac_f32_e32 v105, v229, v120
	v_and_b32_e32 v120, 0xffff0000, v143
	v_fmac_f32_e32 v135, v71, v120
	v_lshlrev_b32_e32 v120, 16, v138
	v_fmac_f32_e32 v146, v230, v120
	v_lshlrev_b32_e32 v120, 16, v142
	v_fmac_f32_e32 v147, v72, v120
	v_and_b32_e32 v120, 0xffff0000, v138
	v_fmac_f32_e32 v104, v231, v120
	v_and_b32_e32 v120, 0xffff0000, v142
	v_fmac_f32_e32 v134, v73, v120
	v_lshlrev_b32_e32 v120, 16, v137
	v_fmac_f32_e32 v148, v224, v120
	v_lshlrev_b32_e32 v120, 16, v141
	v_fmac_f32_e32 v149, v232, v120
	v_and_b32_e32 v120, 0xffff0000, v137
	v_fmac_f32_e32 v103, v225, v120
	v_and_b32_e32 v120, 0xffff0000, v141
	v_fmac_f32_e32 v133, v233, v120
	v_lshlrev_b32_e32 v120, 16, v136
	v_fmac_f32_e32 v151, v226, v120
	v_lshlrev_b32_e32 v120, 16, v140
	v_fmac_f32_e32 v152, v234, v120
	v_and_b32_e32 v120, 0xffff0000, v136
	v_fmac_f32_e32 v102, v227, v120
	v_and_b32_e32 v120, 0xffff0000, v140
	v_fmac_f32_e32 v153, v235, v120
	s_waitcnt vmcnt(7)
	v_cndmask_b32_e64 v86, 0, v204, s[58:59]
	s_waitcnt vmcnt(6)
	v_cndmask_b32_e64 v90, 0, v208, s[58:59]
	v_lshlrev_b32_e32 v120, 16, v86
	v_and_b32_e32 v86, 0xffff0000, v86
	v_cndmask_b32_e64 v87, 0, v205, s[58:59]
	v_fmac_f32_e32 v105, v241, v86
	v_and_b32_e32 v86, 0xffff0000, v90
	v_cndmask_b32_e64 v91, 0, v209, s[58:59]
	v_fmac_f32_e32 v135, v83, v86
	v_lshlrev_b32_e32 v86, 16, v87
	v_fmac_f32_e32 v146, v242, v86
	v_lshlrev_b32_e32 v86, 16, v91
	v_fmac_f32_e32 v147, v84, v86
	v_and_b32_e32 v86, 0xffff0000, v87
	v_cndmask_b32_e64 v88, 0, v206, s[58:59]
	v_fmac_f32_e32 v104, v243, v86
	v_and_b32_e32 v86, 0xffff0000, v91
	v_cndmask_b32_e64 v92, 0, v210, s[58:59]
	v_fmac_f32_e32 v134, v85, v86
	v_lshlrev_b32_e32 v86, 16, v88
	v_fmac_f32_e32 v148, v236, v86
	v_lshlrev_b32_e32 v86, 16, v92
	v_fmac_f32_e32 v149, v244, v86
	v_and_b32_e32 v86, 0xffff0000, v88
	v_cndmask_b32_e64 v89, 0, v207, s[58:59]
	v_fmac_f32_e32 v103, v237, v86
	v_and_b32_e32 v86, 0xffff0000, v92
	v_cndmask_b32_e64 v93, 0, v211, s[58:59]
	v_fmac_f32_e32 v133, v245, v86
	v_lshlrev_b32_e32 v86, 16, v89
	v_fmac_f32_e32 v151, v238, v86
	v_lshlrev_b32_e32 v86, 16, v93
	v_fmac_f32_e32 v144, v240, v120
	v_lshlrev_b32_e32 v120, 16, v90
	v_fmac_f32_e32 v152, v246, v86
	v_and_b32_e32 v86, 0xffff0000, v89
	v_fmac_f32_e32 v145, v82, v120
	v_fmac_f32_e32 v102, v239, v86
	v_and_b32_e32 v86, 0xffff0000, v93
	v_fmac_f32_e32 v153, v247, v86
	v_bfe_u32 v86, v145, 16, 1
	v_add3_u32 v86, v145, v86, s94
	ds_write_b16_d16_hi v101, v86 offset:1536
	v_bfe_u32 v86, v144, 16, 1
	v_add3_u32 v86, v144, v86, s94
	ds_write_b16_d16_hi v101, v86 offset:25600
	v_bfe_u32 v86, v135, 16, 1
	v_add3_u32 v86, v135, v86, s94
	ds_write_b16_d16_hi v101, v86 offset:4608
	v_bfe_u32 v86, v105, 16, 1
	v_add3_u32 v86, v105, v86, s94
	ds_write_b16_d16_hi v101, v86 offset:27648
	v_bfe_u32 v86, v147, 16, 1
	v_add3_u32 v86, v147, v86, s94
	ds_write_b16_d16_hi v101, v86 offset:7680
	v_bfe_u32 v86, v146, 16, 1
	v_add3_u32 v86, v146, v86, s94
	ds_write_b16_d16_hi v101, v86 offset:29696
	v_bfe_u32 v86, v134, 16, 1
	v_add3_u32 v86, v134, v86, s94
	ds_write_b16_d16_hi v101, v86 offset:10752
	v_bfe_u32 v86, v104, 16, 1
	v_add3_u32 v86, v104, v86, s94
	ds_write_b16_d16_hi v101, v86 offset:31744
	v_bfe_u32 v86, v149, 16, 1
	v_add3_u32 v86, v149, v86, s94
	ds_write_b16_d16_hi v101, v86 offset:13824
	v_bfe_u32 v86, v148, 16, 1
	v_add3_u32 v86, v148, v86, s94
	ds_write_b16_d16_hi v101, v86 offset:33792
	v_bfe_u32 v86, v133, 16, 1
	v_add3_u32 v86, v133, v86, s94
	ds_write_b16_d16_hi v101, v86 offset:16896
	v_bfe_u32 v86, v103, 16, 1
	v_add3_u32 v86, v103, v86, s94
	ds_write_b16_d16_hi v101, v86 offset:35840
	v_bfe_u32 v86, v152, 16, 1
	v_add3_u32 v86, v152, v86, s94
	ds_write_b16_d16_hi v101, v86 offset:19968
	v_bfe_u32 v86, v151, 16, 1
	v_add3_u32 v86, v151, v86, s94
	ds_write_b16_d16_hi v101, v86 offset:37888
	v_bfe_u32 v86, v153, 16, 1
	v_add3_u32 v86, v153, v86, s94
	ds_write_b16_d16_hi v101, v86 offset:23040
	v_bfe_u32 v86, v102, 16, 1
	v_add_u32_e32 v104, 0x2ff, v0
	v_add3_u32 v86, v102, v86, s94
	v_med3_i32 v105, v104, 0, v202
	ds_write_b16_d16_hi v101, v86 offset:39936
	v_or_b32_e32 v86, s19, v105
	v_mad_u64_u32 v[102:103], s[44:45], v86, s0, v[106:107]
	s_nop 0
	s_nop 0
	v_add_u32_e32 v120, 0x300, v0
	s_nop 0
	s_nop 0
	s_nop 0
	s_nop 0
	s_nop 0
	v_cmp_eq_u32_e64 s[44:45], v104, v105
	v_med3_i32 v141, v120, 0, v202
	v_add_u32_e32 v149, 0x301, v0
	v_med3_i32 v151, v149, 0, v202
	s_waitcnt vmcnt(5)
	v_cndmask_b32_e64 v136, 0, v46, s[44:45]
	v_or_b32_e32 v86, s19, v141
	v_mad_u64_u32 v[104:105], s[46:47], v86, s0, v[106:107]
	v_cndmask_b32_e64 v135, 0, v47, s[44:45]
	s_nop 0
	s_waitcnt vmcnt(4)
	v_cndmask_b32_e64 v140, 0, v58, s[44:45]
	s_nop 0
	v_cndmask_b32_e64 v139, 0, v59, s[44:45]
	s_nop 0
	s_nop 0
	v_cndmask_b32_e64 v133, 0, v49, s[44:45]
	v_cndmask_b32_e64 v134, 0, v48, s[44:45]
	v_cndmask_b32_e64 v137, 0, v61, s[44:45]
	v_cndmask_b32_e64 v138, 0, v60, s[44:45]
	s_nop 0
	s_nop 0
	s_nop 0
	v_cmp_eq_u32_e64 s[46:47], v120, v141
	s_nop 0
	s_waitcnt vmcnt(3)
	v_cndmask_b32_e64 v144, 0, v62, s[46:47]
	v_or_b32_e32 v86, s19, v151
	v_mad_u64_u32 v[106:107], s[52:53], v86, s0, v[106:107]
	v_cndmask_b32_e64 v143, 0, v63, s[46:47]
	s_nop 0
	s_waitcnt vmcnt(2)
	v_cndmask_b32_e64 v148, 0, v66, s[46:47]
	s_nop 0
	v_cndmask_b32_e64 v147, 0, v67, s[46:47]
	s_nop 0
	s_nop 0
	v_cndmask_b32_e64 v141, 0, v65, s[46:47]
	v_cndmask_b32_e64 v142, 0, v64, s[46:47]
	v_cndmask_b32_e64 v145, 0, v69, s[46:47]
	v_cndmask_b32_e64 v146, 0, v68, s[46:47]
	s_nop 0
	s_nop 0
	s_nop 0
	v_cmp_eq_u32_e64 s[52:53], v149, v151
	v_lshlrev_b32_e32 v149, 16, v136
	v_fma_f32 v34, v50, v149, v34
	v_lshlrev_b32_e32 v50, 16, v140
	v_fma_f32 v30, v54, v50, v212
	v_and_b32_e32 v50, 0xffff0000, v136
	v_fma_f32 v35, v51, v50, v35
	v_and_b32_e32 v50, 0xffff0000, v140
	v_fma_f32 v31, v55, v50, v213
	v_lshlrev_b32_e32 v50, 16, v135
	v_fma_f32 v36, v52, v50, v36
	v_lshlrev_b32_e32 v50, 16, v139
	v_fma_f32 v32, v56, v50, v214
	v_and_b32_e32 v50, 0xffff0000, v135
	v_fmac_f32_e32 v37, v53, v50
	v_and_b32_e32 v50, 0xffff0000, v139
	v_fmac_f32_e32 v215, v57, v50
	v_lshlrev_b32_e32 v50, 16, v134
	v_fma_f32 v26, v38, v50, v216
	v_lshlrev_b32_e32 v38, 16, v138
	v_fma_f32 v22, v220, v38, v172
	v_and_b32_e32 v38, 0xffff0000, v134
	v_fma_f32 v27, v39, v38, v217
	v_and_b32_e32 v38, 0xffff0000, v138
	v_fma_f32 v23, v221, v38, v173
	v_lshlrev_b32_e32 v38, 16, v133
	v_fma_f32 v28, v40, v38, v218
	v_lshlrev_b32_e32 v38, 16, v137
	v_fma_f32 v24, v222, v38, v174
	v_and_b32_e32 v38, 0xffff0000, v133
	v_fmac_f32_e32 v219, v41, v38
	v_and_b32_e32 v38, 0xffff0000, v137
	v_fmac_f32_e32 v175, v223, v38
	v_lshlrev_b32_e32 v38, 16, v144
	v_fmac_f32_e32 v34, v228, v38
	v_lshlrev_b32_e32 v38, 16, v148
	v_fmac_f32_e32 v30, v70, v38
	v_and_b32_e32 v38, 0xffff0000, v144
	v_fmac_f32_e32 v35, v229, v38
	v_and_b32_e32 v38, 0xffff0000, v148
	v_fmac_f32_e32 v31, v71, v38
	v_lshlrev_b32_e32 v38, 16, v143
	v_fmac_f32_e32 v36, v230, v38
	v_lshlrev_b32_e32 v38, 16, v147
	v_fmac_f32_e32 v32, v72, v38
	v_and_b32_e32 v38, 0xffff0000, v143
	v_fmac_f32_e32 v37, v231, v38
	v_and_b32_e32 v38, 0xffff0000, v147
	v_fmac_f32_e32 v215, v73, v38
	v_lshlrev_b32_e32 v38, 16, v142
	v_fmac_f32_e32 v26, v224, v38
	v_lshlrev_b32_e32 v38, 16, v146
	v_fmac_f32_e32 v22, v232, v38
	v_and_b32_e32 v38, 0xffff0000, v142
	v_fmac_f32_e32 v27, v225, v38
	v_and_b32_e32 v38, 0xffff0000, v146
	v_fmac_f32_e32 v23, v233, v38
	v_lshlrev_b32_e32 v38, 16, v141
	v_fmac_f32_e32 v28, v226, v38
	v_lshlrev_b32_e32 v38, 16, v145
	v_fmac_f32_e32 v24, v234, v38
	v_and_b32_e32 v38, 0xffff0000, v141
	v_fmac_f32_e32 v219, v227, v38
	v_and_b32_e32 v38, 0xffff0000, v145
	v_fmac_f32_e32 v175, v235, v38
	s_waitcnt vmcnt(1)
	v_cndmask_b32_e64 v86, 0, v74, s[52:53]
	s_waitcnt vmcnt(0)
	v_cndmask_b32_e64 v90, 0, v78, s[52:53]
	v_lshlrev_b32_e32 v38, 16, v86
	v_fmac_f32_e32 v34, v240, v38
	v_lshlrev_b32_e32 v38, 16, v90
	v_mov_b32_e32 v87, v75
	v_mov_b32_e32 v88, v76
	v_mov_b32_e32 v89, v77
	v_mov_b32_e32 v91, v79
	v_mov_b32_e32 v92, v80
	v_mov_b32_e32 v93, v81
	v_fmac_f32_e32 v30, v82, v38
	v_and_b32_e32 v38, 0xffff0000, v86
	v_cndmask_b32_e64 v87, 0, v87, s[52:53]
	v_fmac_f32_e32 v35, v241, v38
	v_and_b32_e32 v38, 0xffff0000, v90
	v_cndmask_b32_e64 v91, 0, v91, s[52:53]
	v_fmac_f32_e32 v31, v83, v38
	v_lshlrev_b32_e32 v38, 16, v87
	v_fmac_f32_e32 v36, v242, v38
	v_lshlrev_b32_e32 v38, 16, v91
	v_fmac_f32_e32 v32, v84, v38
	v_and_b32_e32 v38, 0xffff0000, v87
	v_cndmask_b32_e64 v88, 0, v88, s[52:53]
	v_fmac_f32_e32 v37, v243, v38
	v_and_b32_e32 v38, 0xffff0000, v91
	v_cndmask_b32_e64 v92, 0, v92, s[52:53]
	v_fmac_f32_e32 v215, v85, v38
	v_lshlrev_b32_e32 v38, 16, v88
	v_fmac_f32_e32 v26, v236, v38
	v_lshlrev_b32_e32 v38, 16, v92
	v_fmac_f32_e32 v22, v244, v38
	v_and_b32_e32 v38, 0xffff0000, v88
	v_cndmask_b32_e64 v89, 0, v89, s[52:53]
	v_fmac_f32_e32 v27, v237, v38
	v_and_b32_e32 v38, 0xffff0000, v92
	v_cndmask_b32_e64 v93, 0, v93, s[52:53]
	v_fmac_f32_e32 v23, v245, v38
	v_lshlrev_b32_e32 v38, 16, v89
	v_fmac_f32_e32 v28, v238, v38
	v_lshlrev_b32_e32 v38, 16, v93
	v_fmac_f32_e32 v24, v246, v38
	v_and_b32_e32 v38, 0xffff0000, v89
	v_fmac_f32_e32 v219, v239, v38
	v_and_b32_e32 v38, 0xffff0000, v93
	v_fmac_f32_e32 v175, v247, v38
	v_bfe_u32 v38, v30, 16, 1
	v_add3_u32 v30, v30, v38, s94
	ds_write_b16_d16_hi v101, v30 offset:2048
	v_bfe_u32 v30, v34, 16, 1
	v_add3_u32 v30, v34, v30, s94
	ds_write_b16_d16_hi v101, v30 offset:26112
	v_bfe_u32 v30, v31, 16, 1
	v_add3_u32 v30, v31, v30, s94
	ds_write_b16_d16_hi v101, v30 offset:5120
	v_bfe_u32 v30, v35, 16, 1
	v_add3_u32 v30, v35, v30, s94
	ds_write_b16_d16_hi v101, v30 offset:28160
	v_bfe_u32 v30, v32, 16, 1
	v_add3_u32 v30, v32, v30, s94
	ds_write_b16_d16_hi v101, v30 offset:8192
	v_bfe_u32 v30, v36, 16, 1
	v_add3_u32 v30, v36, v30, s94
	ds_write_b16_d16_hi v101, v30 offset:30208
	v_bfe_u32 v30, v215, 16, 1
	v_add3_u32 v30, v215, v30, s94
	ds_write_b16_d16_hi v101, v30 offset:11264
	v_bfe_u32 v30, v37, 16, 1
	v_add3_u32 v30, v37, v30, s94
	ds_write_b16_d16_hi v101, v30 offset:32256
	v_bfe_u32 v30, v22, 16, 1
	v_add3_u32 v22, v22, v30, s94
	ds_write_b16_d16_hi v101, v22 offset:14336
	v_bfe_u32 v22, v26, 16, 1
	v_add3_u32 v22, v26, v22, s94
	ds_write_b16_d16_hi v101, v22 offset:34304
	v_bfe_u32 v22, v23, 16, 1
	v_add3_u32 v22, v23, v22, s94
	ds_write_b16_d16_hi v101, v22 offset:17408
	v_bfe_u32 v22, v27, 16, 1
	v_add3_u32 v22, v27, v22, s94
	ds_write_b16_d16_hi v101, v22 offset:36352
	v_bfe_u32 v22, v24, 16, 1
	v_add3_u32 v22, v24, v22, s94
	ds_write_b16_d16_hi v101, v22 offset:20480
	v_bfe_u32 v22, v28, 16, 1
	v_add3_u32 v22, v28, v22, s94
	ds_write_b16_d16_hi v101, v22 offset:38400
	v_bfe_u32 v22, v175, 16, 1
	v_add3_u32 v22, v175, v22, s94
	ds_write_b16_d16_hi v101, v22 offset:23552
	v_bfe_u32 v22, v219, 16, 1
	v_add3_u32 v22, v219, v22, s94
	ds_write_b16_d16_hi v101, v22 offset:40448
	v_mbcnt_hi_u32_b32 v22, -1, v194
	v_and_b32_e32 v23, 64, v22
	v_add_u32_e32 v23, 64, v23
	v_xor_b32_e32 v24, 32, v22
	v_cmp_lt_i32_e32 vcc, v24, v23
	v_lshlrev_b32_e32 v79, 4, v127
	v_add_u32_e32 v65, s17, v126
	v_cndmask_b32_e32 v24, v22, v24, vcc
	v_lshlrev_b32_e32 v71, 2, v24
	v_xor_b32_e32 v24, 16, v22
	v_cmp_lt_i32_e32 vcc, v24, v23
	v_lshlrev_b32_e32 v78, 3, v128
	v_lshl_or_b32 v81, v128, 2, v79
	v_cndmask_b32_e32 v24, v22, v24, vcc
	v_lshlrev_b32_e32 v72, 2, v24
	v_xor_b32_e32 v24, 8, v22
	v_cmp_lt_i32_e32 vcc, v24, v23
	v_add_u32_e32 v70, v65, v160
	v_and_b32_e32 v80, 2, v132
	v_cndmask_b32_e32 v24, v22, v24, vcc
	v_lshlrev_b32_e32 v73, 2, v24
	v_xor_b32_e32 v24, 4, v22
	v_cmp_lt_i32_e32 vcc, v24, v23
	v_lshl_add_u32 v82, v81, 1, s17
	v_lshl_add_u64 v[62:63], s[88:89], 0, v[160:161]
	v_cndmask_b32_e32 v24, v22, v24, vcc
	v_lshlrev_b32_e32 v74, 2, v24
	v_xor_b32_e32 v24, 2, v22
	v_cmp_lt_i32_e32 vcc, v24, v23
	v_sub_u32_e32 v84, v78, v127
	s_waitcnt lgkmcnt(0)
	v_cndmask_b32_e32 v24, v22, v24, vcc
	v_lshlrev_b32_e32 v75, 2, v24
	v_xor_b32_e32 v24, 1, v22
	v_cmp_lt_i32_e32 vcc, v24, v23
	v_and_b32_e32 v23, 48, v125
	v_mov_b32_e32 v25, v175
	v_mov_b32_e32 v29, v219
	v_mov_b32_e32 v33, v215
	v_mov_b32_e32 v42, v220
	v_mov_b32_e32 v43, v221
	v_mov_b32_e32 v44, v222
	v_mov_b32_e32 v45, v223
	v_mov_b32_e32 v46, v224
	v_mov_b32_e32 v47, v225
	v_mov_b32_e32 v48, v226
	v_mov_b32_e32 v49, v227
	v_mov_b32_e32 v58, v232
	v_mov_b32_e32 v59, v233
	v_mov_b32_e32 v60, v234
	v_mov_b32_e32 v61, v235
	v_mov_b32_e32 v64, v238
	v_mov_b32_e32 v66, v228
	v_mov_b32_e32 v67, v229
	v_mov_b32_e32 v68, v230
	v_mov_b32_e32 v69, v231
	v_mov_b32_e32 v76, v246
	v_mov_b32_e32 v77, v247
	s_barrier
	v_cndmask_b32_e32 v22, v22, v24, vcc
	v_lshlrev_b32_e32 v76, 2, v22
	v_or_b32_e32 v22, v130, v129
	v_or_b32_e32 v77, 0x28000, v22
	v_or_b32_e32 v83, 0x20000, v22
	v_lshlrev_b32_e32 v22, 5, v127
	v_add3_u32 v85, v22, v23, s17
